# attention item loop hand-written: LDS-DMA K/V staging (3 stages), K-row permutation so V fragments are single ds_read_b128, bulk fragment reads, exp interleaved with QK MFMAs
# speedup vs baseline: 1.0523x; 1.0523x over previous
.LBB0_350:
	s_lshl_b32 s0, s2, 14
	s_add_u32 s76, s94, s0
	s_addc_u32 s77, s95, 0
	s_add_u32 s76, s76, 0x6bc0000
	s_addc_u32 s77, s77, 0
	s_lshr_b32 s0, s2, 7
	s_mul_i32 s0, s0, 0x108000
	s_add_u32 s78, s94, s0
	s_addc_u32 s79, s95, 0
	s_add_u32 s78, s78, 0x7400000
	s_addc_u32 s79, s79, 0
	s_add_u32 s80, s78, 0x420000
	s_addc_u32 s81, s79, 0
	v_and_b32_e32 v136, 31, v138
	v_bfe_u32 v137, v138, 5, 1
	v_lshrrev_b32_e32 v167, 6, v138
	v_lshl_add_u32 v171, v167, 5, v136
	v_readfirstlane_b32 s83, v167
	v_lshlrev_b32_e32 v171, 7, v171
	v_lshl_add_u32 v171, v137, 4, v171
	s_lshl_b32 s83, s83, 11
	global_load_dwordx4 v[96:99], v171, s[76:77]
	global_load_dwordx4 v[100:103], v171, s[76:77] offset:32
	global_load_dwordx4 v[104:107], v171, s[76:77] offset:64
	global_load_dwordx4 v[108:111], v171, s[76:77] offset:96
	v_and_b32_e32 v168, 0x13, v136
	v_and_b32_e32 v169, 4, v136
	v_lshl_or_b32 v168, v169, 1, v168
	v_and_b32_e32 v169, 8, v136
	v_lshrrev_b32_e32 v169, 1, v169
	v_or_b32_e32 v168, v168, v169
	v_bfe_u32 v170, v168, 1, 3
	v_xor_b32_e32 v170, v170, v137
	v_lshlrev_b32_e32 v170, 4, v170
	v_lshlrev_b32_e32 v168, 7, v168
	v_add_u32_e32 v244, v168, v170
	v_xor_b32_e32 v169, 32, v170
	v_add_u32_e32 v245, v168, v169
	v_xor_b32_e32 v169, 64, v170
	v_add_u32_e32 v246, v168, v169
	v_xor_b32_e32 v169, 96, v170
	v_add_u32_e32 v247, v168, v169
	v_bfe_u32 v170, v136, 1, 3
	v_xor_b32_e32 v170, v170, v137
	v_lshlrev_b32_e32 v170, 4, v170
	v_lshlrev_b32_e32 v168, 7, v136
	v_add_u32_e32 v248, v168, v170
	v_xor_b32_e32 v169, 32, v170
	v_add_u32_e32 v249, v168, v169
	v_xor_b32_e32 v169, 64, v170
	v_add_u32_e32 v250, v168, v169
	v_xor_b32_e32 v169, 96, v170
	v_add_u32_e32 v251, v168, v169
	v_bfe_u32 v168, v138, 3, 3
	v_and_b32_e32 v169, 7, v138
	v_lshrrev_b32_e32 v170, 1, v168
	v_xor_b32_e32 v170, v170, v169
	v_lshl_add_u32 v171, v167, 4, v168
	v_lshlrev_b32_e32 v169, 7, v171
	v_lshl_add_u32 v252, v170, 4, v169
	v_xor_b32_e32 v168, 4, v170
	v_lshl_add_u32 v253, v168, 4, v169
	s_movk_i32 s0, 0x4200
	v_mul_lo_u32 v169, v171, s0
	v_lshl_add_u32 v254, v170, 4, v169
	v_lshl_add_u32 v255, v168, 4, v169
	v_add_u32_e32 v255, 134144, v255
	s_barrier
	s_add_i32 m0, s83, 0
	s_nop 0
	global_load_lds_dwordx4 v252, s[78:79]
	global_load_lds_dwordx4 v253, s[78:79] offset:1024
	s_add_i32 m0, s83, 8192
	s_nop 0
	global_load_lds_dwordx4 v254, s[80:81]
	global_load_lds_dwordx4 v255, s[80:81] offset:1024
	s_add_u32 s78, s78, 0x2000
	s_addc_u32 s79, s79, 0
	s_add_u32 s80, s80, 0x80
	s_addc_u32 s81, s81, 0
	s_add_i32 m0, s83, 16384
	s_nop 0
	global_load_lds_dwordx4 v252, s[78:79]
	global_load_lds_dwordx4 v253, s[78:79] offset:1024
	s_add_i32 m0, s83, 24576
	s_nop 0
	global_load_lds_dwordx4 v254, s[80:81]
	global_load_lds_dwordx4 v255, s[80:81] offset:1024
	s_add_u32 s78, s78, 0x2000
	s_addc_u32 s79, s79, 0
	s_add_u32 s80, s80, 0x80
	s_addc_u32 s81, s81, 0
	v_mov_b32_e32 v32, 0
	v_mov_b32_e32 v33, 0
	v_mov_b32_e32 v34, 0
	v_mov_b32_e32 v35, 0
	v_mov_b32_e32 v36, 0
	v_mov_b32_e32 v37, 0
	v_mov_b32_e32 v38, 0
	v_mov_b32_e32 v39, 0
	v_mov_b32_e32 v40, 0
	v_mov_b32_e32 v41, 0
	v_mov_b32_e32 v42, 0
	v_mov_b32_e32 v43, 0
	v_mov_b32_e32 v44, 0
	v_mov_b32_e32 v45, 0
	v_mov_b32_e32 v46, 0
	v_mov_b32_e32 v47, 0
	v_mov_b32_e32 v48, 0
	v_mov_b32_e32 v49, 0
	v_mov_b32_e32 v50, 0
	v_mov_b32_e32 v51, 0
	v_mov_b32_e32 v52, 0
	v_mov_b32_e32 v53, 0
	v_mov_b32_e32 v54, 0
	v_mov_b32_e32 v55, 0
	v_mov_b32_e32 v56, 0
	v_mov_b32_e32 v57, 0
	v_mov_b32_e32 v58, 0
	v_mov_b32_e32 v59, 0
	v_mov_b32_e32 v60, 0
	v_mov_b32_e32 v61, 0
	v_mov_b32_e32 v62, 0
	v_mov_b32_e32 v63, 0
	v_mov_b32_e32 v128, 0
	v_mov_b32_e32 v129, 0
	s_mov_b32 s84, 0
	s_mov_b32 s82, 44
	s_waitcnt vmcnt(4)
	s_barrier
.Lat_loop:
	ds_read_b128 v[208:211], v244 offset:0
	ds_read_b128 v[212:215], v245 offset:0
	ds_read_b128 v[216:219], v246 offset:0
	ds_read_b128 v[220:223], v247 offset:0
	ds_read_b128 v[224:227], v244 offset:4096
	ds_read_b128 v[228:231], v245 offset:4096
	ds_read_b128 v[232:235], v246 offset:4096
	ds_read_b128 v[236:239], v247 offset:4096
	s_waitcnt lgkmcnt(7)
	v_mfma_f32_32x32x16_bf16 v[0:15], v[208:211], v[96:99], 0
	s_waitcnt lgkmcnt(6)
	v_mfma_f32_32x32x16_bf16 v[0:15], v[212:215], v[100:103], v[0:15]
	s_waitcnt lgkmcnt(5)
	v_mfma_f32_32x32x16_bf16 v[0:15], v[216:219], v[104:107], v[0:15]
	s_waitcnt lgkmcnt(4)
	v_mfma_f32_32x32x16_bf16 v[0:15], v[220:223], v[108:111], v[0:15]
	ds_read_b128 v[176:179], v248 offset:8192
	ds_read_b128 v[180:183], v249 offset:8192
	ds_read_b128 v[184:187], v250 offset:8192
	ds_read_b128 v[188:191], v251 offset:8192
	ds_read_b128 v[192:195], v248 offset:12288
	ds_read_b128 v[196:199], v249 offset:12288
	ds_read_b128 v[200:203], v250 offset:12288
	ds_read_b128 v[240:243], v251 offset:12288
	s_waitcnt lgkmcnt(11)
	v_mfma_f32_32x32x16_bf16 v[16:31], v[224:227], v[96:99], 0
	s_waitcnt lgkmcnt(10)
	v_mfma_f32_32x32x16_bf16 v[16:31], v[228:231], v[100:103], v[16:31]
	s_cmp_lg_u32 s84, 0
	s_cbranch_scc1 .Lat_stab_a0
.Lat_stab_a0_ret:
	v_exp_f32_e32 v64, v0
	v_exp_f32_e32 v65, v1
	v_exp_f32_e32 v66, v2
	v_add_f32_e32 v136, v64, v65
	v_exp_f32_e32 v67, v3
	v_add_f32_e32 v136, v66, v136
	v_exp_f32_e32 v68, v4
	v_add_f32_e32 v136, v67, v136
	v_exp_f32_e32 v69, v5
	v_add_f32_e32 v136, v68, v136
	s_waitcnt lgkmcnt(9)
	v_mfma_f32_32x32x16_bf16 v[16:31], v[232:235], v[104:107], v[16:31]
	v_exp_f32_e32 v70, v6
	v_add_f32_e32 v136, v69, v136
	v_exp_f32_e32 v71, v7
	v_add_f32_e32 v136, v70, v136
	v_exp_f32_e32 v72, v8
	v_add_f32_e32 v136, v71, v136
	v_exp_f32_e32 v73, v9
	v_add_f32_e32 v136, v72, v136
	v_exp_f32_e32 v74, v10
	v_add_f32_e32 v136, v73, v136
	v_exp_f32_e32 v75, v11
	v_add_f32_e32 v136, v74, v136
	v_exp_f32_e32 v76, v12
	v_add_f32_e32 v136, v75, v136
	v_exp_f32_e32 v77, v13
	v_add_f32_e32 v136, v76, v136
	s_waitcnt lgkmcnt(8)
	v_mfma_f32_32x32x16_bf16 v[16:31], v[236:239], v[108:111], v[16:31]
	v_exp_f32_e32 v78, v14
	v_add_f32_e32 v136, v77, v136
	v_exp_f32_e32 v79, v15
	v_add_f32_e32 v136, v78, v136
	s_nop 0
	v_add_f32_e32 v136, v79, v136
	s_add_i32 m0, s83, 32768
	s_nop 0
	global_load_lds_dwordx4 v252, s[78:79]
	global_load_lds_dwordx4 v253, s[78:79] offset:1024
	s_add_i32 m0, s83, 40960
	s_nop 0
	global_load_lds_dwordx4 v254, s[80:81]
	global_load_lds_dwordx4 v255, s[80:81] offset:1024
	s_add_u32 s78, s78, 0x2000
	s_addc_u32 s79, s79, 0
	s_add_u32 s80, s80, 0x80
	s_addc_u32 s81, s81, 0
	s_cmp_lg_u32 s84, 0
	s_cbranch_scc1 .Lat_stab_b0
.Lat_stab_b0_ret:
	v_exp_f32_e32 v80, v16
	v_exp_f32_e32 v81, v17
	v_exp_f32_e32 v82, v18
	v_add_f32_e32 v137, v80, v81
	v_exp_f32_e32 v83, v19
	v_add_f32_e32 v137, v82, v137
	v_exp_f32_e32 v84, v20
	v_add_f32_e32 v137, v83, v137
	v_exp_f32_e32 v85, v21
	v_add_f32_e32 v137, v84, v137
	v_exp_f32_e32 v86, v22
	v_add_f32_e32 v137, v85, v137
	v_exp_f32_e32 v87, v23
	v_add_f32_e32 v137, v86, v137
	v_exp_f32_e32 v88, v24
	v_add_f32_e32 v137, v87, v137
	v_exp_f32_e32 v89, v25
	v_add_f32_e32 v137, v88, v137
	v_exp_f32_e32 v90, v26
	v_add_f32_e32 v137, v89, v137
	v_exp_f32_e32 v91, v27
	v_add_f32_e32 v137, v90, v137
	v_exp_f32_e32 v92, v28
	v_add_f32_e32 v137, v91, v137
	v_exp_f32_e32 v93, v29
	v_add_f32_e32 v137, v92, v137
	v_exp_f32_e32 v94, v30
	v_add_f32_e32 v137, v93, v137
	v_exp_f32_e32 v95, v31
	v_add_f32_e32 v137, v94, v137
	s_nop 0
	v_add_f32_e32 v137, v95, v137
	v_add_f32_e32 v134, v136, v137
	v_cmp_nge_f32_e32 vcc, s65, v134
	v_cmp_gt_f32_e64 s[0:1], s72, v134
	s_or_b64 vcc, vcc, s[0:1]
	s_cbranch_vccnz .Lat_rare0
.Lat_rare0_ret:
	v_cvt_pk_bf16_f32 v112, v64, v65
	v_cvt_pk_bf16_f32 v113, v66, v67
	v_cvt_pk_bf16_f32 v114, v68, v69
	v_cvt_pk_bf16_f32 v115, v70, v71
	v_cvt_pk_bf16_f32 v116, v72, v73
	v_cvt_pk_bf16_f32 v117, v74, v75
	v_cvt_pk_bf16_f32 v118, v76, v77
	v_cvt_pk_bf16_f32 v119, v78, v79
	s_waitcnt lgkmcnt(0)
	v_mfma_f32_32x32x16_bf16 v[32:47], v[176:179], v[112:115], v[32:47]
	v_cvt_pk_bf16_f32 v120, v80, v81
	v_cvt_pk_bf16_f32 v121, v82, v83
	v_mfma_f32_32x32x16_bf16 v[48:63], v[192:195], v[112:115], v[48:63]
	v_cvt_pk_bf16_f32 v122, v84, v85
	v_cvt_pk_bf16_f32 v123, v86, v87
	v_mfma_f32_32x32x16_bf16 v[32:47], v[180:183], v[116:119], v[32:47]
	v_cvt_pk_bf16_f32 v124, v88, v89
	v_cvt_pk_bf16_f32 v125, v90, v91
	v_mfma_f32_32x32x16_bf16 v[48:63], v[196:199], v[116:119], v[48:63]
	v_cvt_pk_bf16_f32 v126, v92, v93
	v_cvt_pk_bf16_f32 v127, v94, v95
	v_mfma_f32_32x32x16_bf16 v[32:47], v[184:187], v[120:123], v[32:47]
	v_mfma_f32_32x32x16_bf16 v[48:63], v[200:203], v[120:123], v[48:63]
	v_mfma_f32_32x32x16_bf16 v[32:47], v[188:191], v[124:127], v[32:47]
	v_mfma_f32_32x32x16_bf16 v[48:63], v[240:243], v[124:127], v[48:63]
	v_add_f32_e32 v128, v128, v134
	s_waitcnt vmcnt(4)
	s_barrier
	ds_read_b128 v[208:211], v244 offset:16384
	ds_read_b128 v[212:215], v245 offset:16384
	ds_read_b128 v[216:219], v246 offset:16384
	ds_read_b128 v[220:223], v247 offset:16384
	ds_read_b128 v[224:227], v244 offset:20480
	ds_read_b128 v[228:231], v245 offset:20480
	ds_read_b128 v[232:235], v246 offset:20480
	ds_read_b128 v[236:239], v247 offset:20480
	s_waitcnt lgkmcnt(7)
	v_mfma_f32_32x32x16_bf16 v[0:15], v[208:211], v[96:99], 0
	s_waitcnt lgkmcnt(6)
	v_mfma_f32_32x32x16_bf16 v[0:15], v[212:215], v[100:103], v[0:15]
	s_waitcnt lgkmcnt(5)
	v_mfma_f32_32x32x16_bf16 v[0:15], v[216:219], v[104:107], v[0:15]
	s_waitcnt lgkmcnt(4)
	v_mfma_f32_32x32x16_bf16 v[0:15], v[220:223], v[108:111], v[0:15]
	ds_read_b128 v[176:179], v248 offset:24576
	ds_read_b128 v[180:183], v249 offset:24576
	ds_read_b128 v[184:187], v250 offset:24576
	ds_read_b128 v[188:191], v251 offset:24576
	ds_read_b128 v[192:195], v248 offset:28672
	ds_read_b128 v[196:199], v249 offset:28672
	ds_read_b128 v[200:203], v250 offset:28672
	ds_read_b128 v[240:243], v251 offset:28672
	s_waitcnt lgkmcnt(11)
	v_mfma_f32_32x32x16_bf16 v[16:31], v[224:227], v[96:99], 0
	s_waitcnt lgkmcnt(10)
	v_mfma_f32_32x32x16_bf16 v[16:31], v[228:231], v[100:103], v[16:31]
	s_cmp_lg_u32 s84, 0
	s_cbranch_scc1 .Lat_stab_a1
.Lat_stab_a1_ret:
	v_exp_f32_e32 v64, v0
	v_exp_f32_e32 v65, v1
	v_exp_f32_e32 v66, v2
	v_add_f32_e32 v136, v64, v65
	v_exp_f32_e32 v67, v3
	v_add_f32_e32 v136, v66, v136
	v_exp_f32_e32 v68, v4
	v_add_f32_e32 v136, v67, v136
	v_exp_f32_e32 v69, v5
	v_add_f32_e32 v136, v68, v136
	s_waitcnt lgkmcnt(9)
	v_mfma_f32_32x32x16_bf16 v[16:31], v[232:235], v[104:107], v[16:31]
	v_exp_f32_e32 v70, v6
	v_add_f32_e32 v136, v69, v136
	v_exp_f32_e32 v71, v7
	v_add_f32_e32 v136, v70, v136
	v_exp_f32_e32 v72, v8
	v_add_f32_e32 v136, v71, v136
	v_exp_f32_e32 v73, v9
	v_add_f32_e32 v136, v72, v136
	v_exp_f32_e32 v74, v10
	v_add_f32_e32 v136, v73, v136
	v_exp_f32_e32 v75, v11
	v_add_f32_e32 v136, v74, v136
	v_exp_f32_e32 v76, v12
	v_add_f32_e32 v136, v75, v136
	v_exp_f32_e32 v77, v13
	v_add_f32_e32 v136, v76, v136
	s_waitcnt lgkmcnt(8)
	v_mfma_f32_32x32x16_bf16 v[16:31], v[236:239], v[108:111], v[16:31]
	v_exp_f32_e32 v78, v14
	v_add_f32_e32 v136, v77, v136
	v_exp_f32_e32 v79, v15
	v_add_f32_e32 v136, v78, v136
	s_nop 0
	v_add_f32_e32 v136, v79, v136
	s_add_i32 m0, s83, 0
	s_nop 0
	global_load_lds_dwordx4 v252, s[78:79]
	global_load_lds_dwordx4 v253, s[78:79] offset:1024
	s_add_i32 m0, s83, 8192
	s_nop 0
	global_load_lds_dwordx4 v254, s[80:81]
	global_load_lds_dwordx4 v255, s[80:81] offset:1024
	s_add_u32 s78, s78, 0x2000
	s_addc_u32 s79, s79, 0
	s_add_u32 s80, s80, 0x80
	s_addc_u32 s81, s81, 0
	s_cmp_lg_u32 s84, 0
	s_cbranch_scc1 .Lat_stab_b1

.Lat_rare1_ret:
	v_cvt_pk_bf16_f32 v112, v64, v65
	v_cvt_pk_bf16_f32 v113, v66, v67
	v_cvt_pk_bf16_f32 v114, v68, v69
	v_cvt_pk_bf16_f32 v115, v70, v71
	v_cvt_pk_bf16_f32 v116, v72, v73
	v_cvt_pk_bf16_f32 v117, v74, v75
	v_cvt_pk_bf16_f32 v118, v76, v77
	v_cvt_pk_bf16_f32 v119, v78, v79
	s_waitcnt lgkmcnt(0)
	v_mfma_f32_32x32x16_bf16 v[32:47], v[176:179], v[112:115], v[32:47]
	v_cvt_pk_bf16_f32 v120, v80, v81
	v_cvt_pk_bf16_f32 v121, v82, v83
	v_mfma_f32_32x32x16_bf16 v[48:63], v[192:195], v[112:115], v[48:63]
	v_cvt_pk_bf16_f32 v122, v84, v85
	v_cvt_pk_bf16_f32 v123, v86, v87
	v_mfma_f32_32x32x16_bf16 v[32:47], v[180:183], v[116:119], v[32:47]
	v_cvt_pk_bf16_f32 v124, v88, v89
	v_cvt_pk_bf16_f32 v125, v90, v91
	v_mfma_f32_32x32x16_bf16 v[48:63], v[196:199], v[116:119], v[48:63]
	v_cvt_pk_bf16_f32 v126, v92, v93
	v_cvt_pk_bf16_f32 v127, v94, v95
	v_mfma_f32_32x32x16_bf16 v[32:47], v[184:187], v[120:123], v[32:47]
	v_mfma_f32_32x32x16_bf16 v[48:63], v[200:203], v[120:123], v[48:63]
	v_mfma_f32_32x32x16_bf16 v[32:47], v[188:191], v[124:127], v[32:47]
	v_mfma_f32_32x32x16_bf16 v[48:63], v[240:243], v[124:127], v[48:63]
	v_add_f32_e32 v128, v128, v134
	s_waitcnt vmcnt(4)
	s_barrier
	ds_read_b128 v[208:211], v244 offset:32768
	ds_read_b128 v[212:215], v245 offset:32768
	ds_read_b128 v[216:219], v246 offset:32768
	ds_read_b128 v[220:223], v247 offset:32768
	ds_read_b128 v[224:227], v244 offset:36864
	ds_read_b128 v[228:231], v245 offset:36864
	ds_read_b128 v[232:235], v246 offset:36864
	ds_read_b128 v[236:239], v247 offset:36864
	s_waitcnt lgkmcnt(7)
	v_mfma_f32_32x32x16_bf16 v[0:15], v[208:211], v[96:99], 0
	s_waitcnt lgkmcnt(6)
	v_mfma_f32_32x32x16_bf16 v[0:15], v[212:215], v[100:103], v[0:15]
	s_waitcnt lgkmcnt(5)
	v_mfma_f32_32x32x16_bf16 v[0:15], v[216:219], v[104:107], v[0:15]
	s_waitcnt lgkmcnt(4)
	v_mfma_f32_32x32x16_bf16 v[0:15], v[220:223], v[108:111], v[0:15]
	ds_read_b128 v[176:179], v248 offset:40960
	ds_read_b128 v[180:183], v249 offset:40960
	ds_read_b128 v[184:187], v250 offset:40960
	ds_read_b128 v[188:191], v251 offset:40960
	ds_read_b128 v[192:195], v248 offset:45056
	ds_read_b128 v[196:199], v249 offset:45056
	ds_read_b128 v[200:203], v250 offset:45056
	ds_read_b128 v[240:243], v251 offset:45056
	s_waitcnt lgkmcnt(11)
	v_mfma_f32_32x32x16_bf16 v[16:31], v[224:227], v[96:99], 0
	s_waitcnt lgkmcnt(10)
	v_mfma_f32_32x32x16_bf16 v[16:31], v[228:231], v[100:103], v[16:31]
	s_cmp_lg_u32 s84, 0
	s_cbranch_scc1 .Lat_stab_a2
.Lat_stab_a2_ret:
	v_exp_f32_e32 v64, v0
	v_exp_f32_e32 v65, v1
	v_exp_f32_e32 v66, v2
	v_add_f32_e32 v136, v64, v65
	v_exp_f32_e32 v67, v3
	v_add_f32_e32 v136, v66, v136
	v_exp_f32_e32 v68, v4
	v_add_f32_e32 v136, v67, v136
	v_exp_f32_e32 v69, v5
	v_add_f32_e32 v136, v68, v136
	s_waitcnt lgkmcnt(9)
	v_mfma_f32_32x32x16_bf16 v[16:31], v[232:235], v[104:107], v[16:31]
	v_exp_f32_e32 v70, v6
	v_add_f32_e32 v136, v69, v136
	v_exp_f32_e32 v71, v7
	v_add_f32_e32 v136, v70, v136
	v_exp_f32_e32 v72, v8
	v_add_f32_e32 v136, v71, v136
	v_exp_f32_e32 v73, v9
	v_add_f32_e32 v136, v72, v136
	v_exp_f32_e32 v74, v10
	v_add_f32_e32 v136, v73, v136
	v_exp_f32_e32 v75, v11
	v_add_f32_e32 v136, v74, v136
	v_exp_f32_e32 v76, v12
	v_add_f32_e32 v136, v75, v136
	v_exp_f32_e32 v77, v13
	v_add_f32_e32 v136, v76, v136
	s_waitcnt lgkmcnt(8)
	v_mfma_f32_32x32x16_bf16 v[16:31], v[236:239], v[108:111], v[16:31]
	v_exp_f32_e32 v78, v14
	v_add_f32_e32 v136, v77, v136
	v_exp_f32_e32 v79, v15
	v_add_f32_e32 v136, v78, v136
	s_nop 0
	v_add_f32_e32 v136, v79, v136
	s_add_i32 m0, s83, 16384
	s_nop 0
	global_load_lds_dwordx4 v252, s[78:79]
	global_load_lds_dwordx4 v253, s[78:79] offset:1024
	s_add_i32 m0, s83, 24576
	s_nop 0
	global_load_lds_dwordx4 v254, s[80:81]
	global_load_lds_dwordx4 v255, s[80:81] offset:1024
	s_add_u32 s78, s78, 0x2000
	s_addc_u32 s79, s79, 0
	s_add_u32 s80, s80, 0x80
	s_addc_u32 s81, s81, 0
	s_cmp_lg_u32 s84, 0
	s_cbranch_scc1 .Lat_stab_b2

.Lat_rare2_ret:
	v_cvt_pk_bf16_f32 v112, v64, v65
	v_cvt_pk_bf16_f32 v113, v66, v67
	v_cvt_pk_bf16_f32 v114, v68, v69
	v_cvt_pk_bf16_f32 v115, v70, v71
	v_cvt_pk_bf16_f32 v116, v72, v73
	v_cvt_pk_bf16_f32 v117, v74, v75
	v_cvt_pk_bf16_f32 v118, v76, v77
	v_cvt_pk_bf16_f32 v119, v78, v79
	s_waitcnt lgkmcnt(0)
	v_mfma_f32_32x32x16_bf16 v[32:47], v[176:179], v[112:115], v[32:47]
	v_cvt_pk_bf16_f32 v120, v80, v81
	v_cvt_pk_bf16_f32 v121, v82, v83
	v_mfma_f32_32x32x16_bf16 v[48:63], v[192:195], v[112:115], v[48:63]
	v_cvt_pk_bf16_f32 v122, v84, v85
	v_cvt_pk_bf16_f32 v123, v86, v87
	v_mfma_f32_32x32x16_bf16 v[32:47], v[180:183], v[116:119], v[32:47]
	v_cvt_pk_bf16_f32 v124, v88, v89
	v_cvt_pk_bf16_f32 v125, v90, v91
	v_mfma_f32_32x32x16_bf16 v[48:63], v[196:199], v[116:119], v[48:63]
	v_cvt_pk_bf16_f32 v126, v92, v93
	v_cvt_pk_bf16_f32 v127, v94, v95
	v_mfma_f32_32x32x16_bf16 v[32:47], v[184:187], v[120:123], v[32:47]
	v_mfma_f32_32x32x16_bf16 v[48:63], v[200:203], v[120:123], v[48:63]
	v_mfma_f32_32x32x16_bf16 v[32:47], v[188:191], v[124:127], v[32:47]
	v_mfma_f32_32x32x16_bf16 v[48:63], v[240:243], v[124:127], v[48:63]
	v_add_f32_e32 v128, v128, v134
	s_waitcnt vmcnt(4)
	s_barrier
	s_sub_u32 s82, s82, 1
	s_cmp_lg_u32 s82, 0
	s_cbranch_scc1 .Lat_loop
	s_waitcnt vmcnt(0)
	s_lshr_b32 s0, s2, 8
	s_lshl_b32 s0, s0, 13
	s_and_b32 s1, s2, 63
	s_lshl_b32 s1, s1, 7
	s_or_b32 s0, s0, s1
	s_bfe_u32 s1, s2, 0x20006
	s_lshl_b32 s1, s1, 7
	s_add_u32 s86, s94, 0x3200000
	s_addc_u32 s87, s95, 0
	s_add_u32 s88, s94, 0x1100200
	s_addc_u32 s89, s95, 0
	v_lshrrev_b32_e32 v0, 1, v138
	v_and_b32_e32 v0, 0xe0, v0
	v_and_or_b32 v0, v138, 31, v0
	v_add_u32_e32 v0, s0, v0
	v_bfe_u32 v3, v138, 5, 1
	v_lshl_add_u32 v3, v3, 3, s1
	v_mul_lo_u32 v1, v0, s64
	v_add_u32_e32 v1, v1, v3
	v_lshl_add_u32 v2, v0, 11, v3
	global_load_dwordx2 v[64:65], v1, s[86:87]
	global_load_dwordx2 v[66:67], v1, s[86:87] offset:16
	global_load_dwordx2 v[68:69], v1, s[86:87] offset:32
	global_load_dwordx2 v[70:71], v1, s[86:87] offset:48
	global_load_dwordx2 v[72:73], v1, s[86:87] offset:64
	global_load_dwordx2 v[74:75], v1, s[86:87] offset:80
	global_load_dwordx2 v[76:77], v1, s[86:87] offset:96
	global_load_dwordx2 v[78:79], v1, s[86:87] offset:112
	v_mbcnt_lo_u32_b32 v4, -1, 0
	v_mbcnt_hi_u32_b32 v4, -1, v4
	v_xor_b32_e32 v4, 32, v4
	v_lshlrev_b32_e32 v4, 2, v4
	ds_bpermute_b32 v5, v4, v128
	s_waitcnt lgkmcnt(0)
	v_add_f32_e32 v5, v128, v5
	v_mov_b32_e32 v7, 1.0
	v_div_scale_f32 v8, s[0:1], v5, v5, v7
	v_rcp_f32_e32 v9, v8
	s_nop 0
	v_fma_f32 v10, -v8, v9, 1.0
	v_fmac_f32_e32 v9, v10, v9
	v_div_scale_f32 v10, vcc, v7, v5, v7
	v_mul_f32_e32 v11, v10, v9
	v_fma_f32 v12, -v8, v11, v10
	v_fmac_f32_e32 v11, v12, v9
	v_fma_f32 v8, -v8, v11, v10
	v_div_fmas_f32 v8, v8, v9, v11
	v_div_fixup_f32 v6, v8, v5, v7
	s_waitcnt vmcnt(7)
	v_lshlrev_b32_e32 v16, 16, v64
	v_and_b32_e32 v17, 0xffff0000, v64
	v_lshlrev_b32_e32 v18, 16, v65
	v_and_b32_e32 v19, 0xffff0000, v65
	v_mul_f32_e32 v20, 0xbfb8aa3b, v16
	v_mul_f32_e32 v21, 0xbfb8aa3b, v17
	v_mul_f32_e32 v22, 0xbfb8aa3b, v18
	v_mul_f32_e32 v23, 0xbfb8aa3b, v19
	v_exp_f32_e32 v20, v20
	v_exp_f32_e32 v21, v21
	v_exp_f32_e32 v22, v22
	v_exp_f32_e32 v23, v23
	s_nop 0
	v_add_f32_e32 v20, 1.0, v20
	v_add_f32_e32 v21, 1.0, v21
	v_add_f32_e32 v22, 1.0, v22
	v_add_f32_e32 v23, 1.0, v23
	v_div_scale_f32 v8, s[0:1], v20, v20, v16
	v_rcp_f32_e32 v9, v8
	s_nop 0
	v_fma_f32 v10, -v8, v9, 1.0
	v_fmac_f32_e32 v9, v10, v9
	v_div_scale_f32 v10, vcc, v16, v20, v16
	v_mul_f32_e32 v11, v10, v9
	v_fma_f32 v12, -v8, v11, v10
	v_fmac_f32_e32 v11, v12, v9
	v_fma_f32 v8, -v8, v11, v10
	v_div_fmas_f32 v8, v8, v9, v11
	v_div_fixup_f32 v24, v8, v20, v16
	v_div_scale_f32 v8, s[0:1], v21, v21, v17
	v_rcp_f32_e32 v9, v8
	s_nop 0
	v_fma_f32 v10, -v8, v9, 1.0
	v_fmac_f32_e32 v9, v10, v9
	v_div_scale_f32 v10, vcc, v17, v21, v17
	v_mul_f32_e32 v11, v10, v9
	v_fma_f32 v12, -v8, v11, v10
	v_fmac_f32_e32 v11, v12, v9
	v_fma_f32 v8, -v8, v11, v10
	v_div_fmas_f32 v8, v8, v9, v11
	v_div_fixup_f32 v25, v8, v21, v17
	v_div_scale_f32 v8, s[0:1], v22, v22, v18
	v_rcp_f32_e32 v9, v8
	s_nop 0
	v_fma_f32 v10, -v8, v9, 1.0
	v_fmac_f32_e32 v9, v10, v9
	v_div_scale_f32 v10, vcc, v18, v22, v18
	v_mul_f32_e32 v11, v10, v9
	v_fma_f32 v12, -v8, v11, v10
	v_fmac_f32_e32 v11, v12, v9
	v_fma_f32 v8, -v8, v11, v10
	v_div_fmas_f32 v8, v8, v9, v11
	v_div_fixup_f32 v26, v8, v22, v18
	v_div_scale_f32 v8, s[0:1], v23, v23, v19
	v_rcp_f32_e32 v9, v8
	s_nop 0
	v_fma_f32 v10, -v8, v9, 1.0
	v_fmac_f32_e32 v9, v10, v9
	v_div_scale_f32 v10, vcc, v19, v23, v19
	v_mul_f32_e32 v11, v10, v9
	v_fma_f32 v12, -v8, v11, v10
	v_fmac_f32_e32 v11, v12, v9
	v_fma_f32 v8, -v8, v11, v10
	v_div_fmas_f32 v8, v8, v9, v11
	v_div_fixup_f32 v27, v8, v23, v19
	v_mul_f32_e32 v24, v24, v32
	v_mul_f32_e32 v25, v25, v33
	v_mul_f32_e32 v26, v26, v34
	v_mul_f32_e32 v27, v27, v35
	v_mul_f32_e32 v24, v24, v6
	v_mul_f32_e32 v25, v25, v6
	v_mul_f32_e32 v26, v26, v6
	v_mul_f32_e32 v27, v27, v6
	v_cvt_pk_bf16_f32 v28, v24, v25
	v_cvt_pk_bf16_f32 v29, v26, v27
	global_store_dwordx2 v2, v[28:29], s[88:89]
	s_waitcnt vmcnt(7)
	v_lshlrev_b32_e32 v16, 16, v66
	v_and_b32_e32 v17, 0xffff0000, v66
	v_lshlrev_b32_e32 v18, 16, v67
	v_and_b32_e32 v19, 0xffff0000, v67
	v_mul_f32_e32 v20, 0xbfb8aa3b, v16
	v_mul_f32_e32 v21, 0xbfb8aa3b, v17
	v_mul_f32_e32 v22, 0xbfb8aa3b, v18
	v_mul_f32_e32 v23, 0xbfb8aa3b, v19
	v_exp_f32_e32 v20, v20
	v_exp_f32_e32 v21, v21
	v_exp_f32_e32 v22, v22
	v_exp_f32_e32 v23, v23
	s_nop 0
	v_add_f32_e32 v20, 1.0, v20
	v_add_f32_e32 v21, 1.0, v21
	v_add_f32_e32 v22, 1.0, v22
	v_add_f32_e32 v23, 1.0, v23
	v_div_scale_f32 v8, s[0:1], v20, v20, v16
	v_rcp_f32_e32 v9, v8
	s_nop 0
	v_fma_f32 v10, -v8, v9, 1.0
	v_fmac_f32_e32 v9, v10, v9
	v_div_scale_f32 v10, vcc, v16, v20, v16
	v_mul_f32_e32 v11, v10, v9
	v_fma_f32 v12, -v8, v11, v10
	v_fmac_f32_e32 v11, v12, v9
	v_fma_f32 v8, -v8, v11, v10
	v_div_fmas_f32 v8, v8, v9, v11
	v_div_fixup_f32 v24, v8, v20, v16
	v_div_scale_f32 v8, s[0:1], v21, v21, v17
	v_rcp_f32_e32 v9, v8
	s_nop 0
	v_fma_f32 v10, -v8, v9, 1.0
	v_fmac_f32_e32 v9, v10, v9
	v_div_scale_f32 v10, vcc, v17, v21, v17
	v_mul_f32_e32 v11, v10, v9
	v_fma_f32 v12, -v8, v11, v10
	v_fmac_f32_e32 v11, v12, v9
	v_fma_f32 v8, -v8, v11, v10
	v_div_fmas_f32 v8, v8, v9, v11
	v_div_fixup_f32 v25, v8, v21, v17
	v_div_scale_f32 v8, s[0:1], v22, v22, v18
	v_rcp_f32_e32 v9, v8
	s_nop 0
	v_fma_f32 v10, -v8, v9, 1.0
	v_fmac_f32_e32 v9, v10, v9
	v_div_scale_f32 v10, vcc, v18, v22, v18
	v_mul_f32_e32 v11, v10, v9
	v_fma_f32 v12, -v8, v11, v10
	v_fmac_f32_e32 v11, v12, v9
	v_fma_f32 v8, -v8, v11, v10
	v_div_fmas_f32 v8, v8, v9, v11
	v_div_fixup_f32 v26, v8, v22, v18
	v_div_scale_f32 v8, s[0:1], v23, v23, v19
	v_rcp_f32_e32 v9, v8
	s_nop 0
	v_fma_f32 v10, -v8, v9, 1.0
	v_fmac_f32_e32 v9, v10, v9
	v_div_scale_f32 v10, vcc, v19, v23, v19
	v_mul_f32_e32 v11, v10, v9
	v_fma_f32 v12, -v8, v11, v10
	v_fmac_f32_e32 v11, v12, v9
	v_fma_f32 v8, -v8, v11, v10
	v_div_fmas_f32 v8, v8, v9, v11
	v_div_fixup_f32 v27, v8, v23, v19
	v_mul_f32_e32 v24, v24, v36
	v_mul_f32_e32 v25, v25, v37
	v_mul_f32_e32 v26, v26, v38
	v_mul_f32_e32 v27, v27, v39
	v_mul_f32_e32 v24, v24, v6
	v_mul_f32_e32 v25, v25, v6
	v_mul_f32_e32 v26, v26, v6
	v_mul_f32_e32 v27, v27, v6
	v_cvt_pk_bf16_f32 v30, v24, v25
	v_cvt_pk_bf16_f32 v31, v26, v27
	global_store_dwordx2 v2, v[30:31], s[88:89] offset:16
	s_waitcnt vmcnt(7)
	v_lshlrev_b32_e32 v16, 16, v68
	v_and_b32_e32 v17, 0xffff0000, v68
	v_lshlrev_b32_e32 v18, 16, v69
	v_and_b32_e32 v19, 0xffff0000, v69
	v_mul_f32_e32 v20, 0xbfb8aa3b, v16
	v_mul_f32_e32 v21, 0xbfb8aa3b, v17
	v_mul_f32_e32 v22, 0xbfb8aa3b, v18
	v_mul_f32_e32 v23, 0xbfb8aa3b, v19
	v_exp_f32_e32 v20, v20
	v_exp_f32_e32 v21, v21
	v_exp_f32_e32 v22, v22
	v_exp_f32_e32 v23, v23
	s_nop 0
	v_add_f32_e32 v20, 1.0, v20
	v_add_f32_e32 v21, 1.0, v21
	v_add_f32_e32 v22, 1.0, v22
	v_add_f32_e32 v23, 1.0, v23
	v_div_scale_f32 v8, s[0:1], v20, v20, v16
	v_rcp_f32_e32 v9, v8
	s_nop 0
	v_fma_f32 v10, -v8, v9, 1.0
	v_fmac_f32_e32 v9, v10, v9
	v_div_scale_f32 v10, vcc, v16, v20, v16
	v_mul_f32_e32 v11, v10, v9
	v_fma_f32 v12, -v8, v11, v10
	v_fmac_f32_e32 v11, v12, v9
	v_fma_f32 v8, -v8, v11, v10
	v_div_fmas_f32 v8, v8, v9, v11
	v_div_fixup_f32 v24, v8, v20, v16
	v_div_scale_f32 v8, s[0:1], v21, v21, v17
	v_rcp_f32_e32 v9, v8
	s_nop 0
	v_fma_f32 v10, -v8, v9, 1.0
	v_fmac_f32_e32 v9, v10, v9
	v_div_scale_f32 v10, vcc, v17, v21, v17
	v_mul_f32_e32 v11, v10, v9
	v_fma_f32 v12, -v8, v11, v10
	v_fmac_f32_e32 v11, v12, v9
	v_fma_f32 v8, -v8, v11, v10
	v_div_fmas_f32 v8, v8, v9, v11
	v_div_fixup_f32 v25, v8, v21, v17
	v_div_scale_f32 v8, s[0:1], v22, v22, v18
	v_rcp_f32_e32 v9, v8
	s_nop 0
	v_fma_f32 v10, -v8, v9, 1.0
	v_fmac_f32_e32 v9, v10, v9
	v_div_scale_f32 v10, vcc, v18, v22, v18
	v_mul_f32_e32 v11, v10, v9
	v_fma_f32 v12, -v8, v11, v10
	v_fmac_f32_e32 v11, v12, v9
	v_fma_f32 v8, -v8, v11, v10
	v_div_fmas_f32 v8, v8, v9, v11
	v_div_fixup_f32 v26, v8, v22, v18
	v_div_scale_f32 v8, s[0:1], v23, v23, v19
	v_rcp_f32_e32 v9, v8
	s_nop 0
	v_fma_f32 v10, -v8, v9, 1.0
	v_fmac_f32_e32 v9, v10, v9
	v_div_scale_f32 v10, vcc, v19, v23, v19
	v_mul_f32_e32 v11, v10, v9
	v_fma_f32 v12, -v8, v11, v10
	v_fmac_f32_e32 v11, v12, v9
	v_fma_f32 v8, -v8, v11, v10
	v_div_fmas_f32 v8, v8, v9, v11
	v_div_fixup_f32 v27, v8, v23, v19
	v_mul_f32_e32 v24, v24, v40
	v_mul_f32_e32 v25, v25, v41
	v_mul_f32_e32 v26, v26, v42
	v_mul_f32_e32 v27, v27, v43
	v_mul_f32_e32 v24, v24, v6
	v_mul_f32_e32 v25, v25, v6
	v_mul_f32_e32 v26, v26, v6
	v_mul_f32_e32 v27, v27, v6
	v_cvt_pk_bf16_f32 v28, v24, v25
	v_cvt_pk_bf16_f32 v29, v26, v27
	global_store_dwordx2 v2, v[28:29], s[88:89] offset:32
	s_waitcnt vmcnt(7)
	v_lshlrev_b32_e32 v16, 16, v70
	v_and_b32_e32 v17, 0xffff0000, v70
	v_lshlrev_b32_e32 v18, 16, v71
	v_and_b32_e32 v19, 0xffff0000, v71
	v_mul_f32_e32 v20, 0xbfb8aa3b, v16
	v_mul_f32_e32 v21, 0xbfb8aa3b, v17
	v_mul_f32_e32 v22, 0xbfb8aa3b, v18
	v_mul_f32_e32 v23, 0xbfb8aa3b, v19
	v_exp_f32_e32 v20, v20
	v_exp_f32_e32 v21, v21
	v_exp_f32_e32 v22, v22
	v_exp_f32_e32 v23, v23
	s_nop 0
	v_add_f32_e32 v20, 1.0, v20
	v_add_f32_e32 v21, 1.0, v21
	v_add_f32_e32 v22, 1.0, v22
	v_add_f32_e32 v23, 1.0, v23
	v_div_scale_f32 v8, s[0:1], v20, v20, v16
	v_rcp_f32_e32 v9, v8
	s_nop 0
	v_fma_f32 v10, -v8, v9, 1.0
	v_fmac_f32_e32 v9, v10, v9
	v_div_scale_f32 v10, vcc, v16, v20, v16
	v_mul_f32_e32 v11, v10, v9
	v_fma_f32 v12, -v8, v11, v10
	v_fmac_f32_e32 v11, v12, v9
	v_fma_f32 v8, -v8, v11, v10
	v_div_fmas_f32 v8, v8, v9, v11
	v_div_fixup_f32 v24, v8, v20, v16
	v_div_scale_f32 v8, s[0:1], v21, v21, v17
	v_rcp_f32_e32 v9, v8
	s_nop 0
	v_fma_f32 v10, -v8, v9, 1.0
	v_fmac_f32_e32 v9, v10, v9
	v_div_scale_f32 v10, vcc, v17, v21, v17
	v_mul_f32_e32 v11, v10, v9
	v_fma_f32 v12, -v8, v11, v10
	v_fmac_f32_e32 v11, v12, v9
	v_fma_f32 v8, -v8, v11, v10
	v_div_fmas_f32 v8, v8, v9, v11
	v_div_fixup_f32 v25, v8, v21, v17
	v_div_scale_f32 v8, s[0:1], v22, v22, v18
	v_rcp_f32_e32 v9, v8
	s_nop 0
	v_fma_f32 v10, -v8, v9, 1.0
	v_fmac_f32_e32 v9, v10, v9
	v_div_scale_f32 v10, vcc, v18, v22, v18
	v_mul_f32_e32 v11, v10, v9
	v_fma_f32 v12, -v8, v11, v10
	v_fmac_f32_e32 v11, v12, v9
	v_fma_f32 v8, -v8, v11, v10
	v_div_fmas_f32 v8, v8, v9, v11
	v_div_fixup_f32 v26, v8, v22, v18
	v_div_scale_f32 v8, s[0:1], v23, v23, v19
	v_rcp_f32_e32 v9, v8
	s_nop 0
	v_fma_f32 v10, -v8, v9, 1.0
	v_fmac_f32_e32 v9, v10, v9
	v_div_scale_f32 v10, vcc, v19, v23, v19
	v_mul_f32_e32 v11, v10, v9
	v_fma_f32 v12, -v8, v11, v10
	v_fmac_f32_e32 v11, v12, v9
	v_fma_f32 v8, -v8, v11, v10
	v_div_fmas_f32 v8, v8, v9, v11
	v_div_fixup_f32 v27, v8, v23, v19
	v_mul_f32_e32 v24, v24, v44
	v_mul_f32_e32 v25, v25, v45
	v_mul_f32_e32 v26, v26, v46
	v_mul_f32_e32 v27, v27, v47
	v_mul_f32_e32 v24, v24, v6
	v_mul_f32_e32 v25, v25, v6
	v_mul_f32_e32 v26, v26, v6
	v_mul_f32_e32 v27, v27, v6
	v_cvt_pk_bf16_f32 v30, v24, v25
	v_cvt_pk_bf16_f32 v31, v26, v27
	global_store_dwordx2 v2, v[30:31], s[88:89] offset:48
	s_waitcnt vmcnt(7)
	v_lshlrev_b32_e32 v16, 16, v72
	v_and_b32_e32 v17, 0xffff0000, v72
	v_lshlrev_b32_e32 v18, 16, v73
	v_and_b32_e32 v19, 0xffff0000, v73
	v_mul_f32_e32 v20, 0xbfb8aa3b, v16
	v_mul_f32_e32 v21, 0xbfb8aa3b, v17
	v_mul_f32_e32 v22, 0xbfb8aa3b, v18
	v_mul_f32_e32 v23, 0xbfb8aa3b, v19
	v_exp_f32_e32 v20, v20
	v_exp_f32_e32 v21, v21
	v_exp_f32_e32 v22, v22
	v_exp_f32_e32 v23, v23
	s_nop 0
	v_add_f32_e32 v20, 1.0, v20
	v_add_f32_e32 v21, 1.0, v21
	v_add_f32_e32 v22, 1.0, v22
	v_add_f32_e32 v23, 1.0, v23
	v_div_scale_f32 v8, s[0:1], v20, v20, v16
	v_rcp_f32_e32 v9, v8
	s_nop 0
	v_fma_f32 v10, -v8, v9, 1.0
	v_fmac_f32_e32 v9, v10, v9
	v_div_scale_f32 v10, vcc, v16, v20, v16
	v_mul_f32_e32 v11, v10, v9
	v_fma_f32 v12, -v8, v11, v10
	v_fmac_f32_e32 v11, v12, v9
	v_fma_f32 v8, -v8, v11, v10
	v_div_fmas_f32 v8, v8, v9, v11
	v_div_fixup_f32 v24, v8, v20, v16
	v_div_scale_f32 v8, s[0:1], v21, v21, v17
	v_rcp_f32_e32 v9, v8
	s_nop 0
	v_fma_f32 v10, -v8, v9, 1.0
	v_fmac_f32_e32 v9, v10, v9
	v_div_scale_f32 v10, vcc, v17, v21, v17
	v_mul_f32_e32 v11, v10, v9
	v_fma_f32 v12, -v8, v11, v10
	v_fmac_f32_e32 v11, v12, v9
	v_fma_f32 v8, -v8, v11, v10
	v_div_fmas_f32 v8, v8, v9, v11
	v_div_fixup_f32 v25, v8, v21, v17
	v_div_scale_f32 v8, s[0:1], v22, v22, v18
	v_rcp_f32_e32 v9, v8
	s_nop 0
	v_fma_f32 v10, -v8, v9, 1.0
	v_fmac_f32_e32 v9, v10, v9
	v_div_scale_f32 v10, vcc, v18, v22, v18
	v_mul_f32_e32 v11, v10, v9
	v_fma_f32 v12, -v8, v11, v10
	v_fmac_f32_e32 v11, v12, v9
	v_fma_f32 v8, -v8, v11, v10
	v_div_fmas_f32 v8, v8, v9, v11
	v_div_fixup_f32 v26, v8, v22, v18
	v_div_scale_f32 v8, s[0:1], v23, v23, v19
	v_rcp_f32_e32 v9, v8
	s_nop 0
	v_fma_f32 v10, -v8, v9, 1.0
	v_fmac_f32_e32 v9, v10, v9
	v_div_scale_f32 v10, vcc, v19, v23, v19
	v_mul_f32_e32 v11, v10, v9
	v_fma_f32 v12, -v8, v11, v10
	v_fmac_f32_e32 v11, v12, v9
	v_fma_f32 v8, -v8, v11, v10
	v_div_fmas_f32 v8, v8, v9, v11
	v_div_fixup_f32 v27, v8, v23, v19
	v_mul_f32_e32 v24, v24, v48
	v_mul_f32_e32 v25, v25, v49
	v_mul_f32_e32 v26, v26, v50
	v_mul_f32_e32 v27, v27, v51
	v_mul_f32_e32 v24, v24, v6
	v_mul_f32_e32 v25, v25, v6
	v_mul_f32_e32 v26, v26, v6
	v_mul_f32_e32 v27, v27, v6
	v_cvt_pk_bf16_f32 v28, v24, v25
	v_cvt_pk_bf16_f32 v29, v26, v27
	global_store_dwordx2 v2, v[28:29], s[88:89] offset:64
	s_waitcnt vmcnt(7)
	v_lshlrev_b32_e32 v16, 16, v74
	v_and_b32_e32 v17, 0xffff0000, v74
	v_lshlrev_b32_e32 v18, 16, v75
	v_and_b32_e32 v19, 0xffff0000, v75
	v_mul_f32_e32 v20, 0xbfb8aa3b, v16
	v_mul_f32_e32 v21, 0xbfb8aa3b, v17
	v_mul_f32_e32 v22, 0xbfb8aa3b, v18
	v_mul_f32_e32 v23, 0xbfb8aa3b, v19
	v_exp_f32_e32 v20, v20
	v_exp_f32_e32 v21, v21
	v_exp_f32_e32 v22, v22
	v_exp_f32_e32 v23, v23
	s_nop 0
	v_add_f32_e32 v20, 1.0, v20
	v_add_f32_e32 v21, 1.0, v21
	v_add_f32_e32 v22, 1.0, v22
	v_add_f32_e32 v23, 1.0, v23
	v_div_scale_f32 v8, s[0:1], v20, v20, v16
	v_rcp_f32_e32 v9, v8
	s_nop 0
	v_fma_f32 v10, -v8, v9, 1.0
	v_fmac_f32_e32 v9, v10, v9
	v_div_scale_f32 v10, vcc, v16, v20, v16
	v_mul_f32_e32 v11, v10, v9
	v_fma_f32 v12, -v8, v11, v10
	v_fmac_f32_e32 v11, v12, v9
	v_fma_f32 v8, -v8, v11, v10
	v_div_fmas_f32 v8, v8, v9, v11
	v_div_fixup_f32 v24, v8, v20, v16
	v_div_scale_f32 v8, s[0:1], v21, v21, v17
	v_rcp_f32_e32 v9, v8
	s_nop 0
	v_fma_f32 v10, -v8, v9, 1.0
	v_fmac_f32_e32 v9, v10, v9
	v_div_scale_f32 v10, vcc, v17, v21, v17
	v_mul_f32_e32 v11, v10, v9
	v_fma_f32 v12, -v8, v11, v10
	v_fmac_f32_e32 v11, v12, v9
	v_fma_f32 v8, -v8, v11, v10
	v_div_fmas_f32 v8, v8, v9, v11
	v_div_fixup_f32 v25, v8, v21, v17
	v_div_scale_f32 v8, s[0:1], v22, v22, v18
	v_rcp_f32_e32 v9, v8
	s_nop 0
	v_fma_f32 v10, -v8, v9, 1.0
	v_fmac_f32_e32 v9, v10, v9
	v_div_scale_f32 v10, vcc, v18, v22, v18
	v_mul_f32_e32 v11, v10, v9
	v_fma_f32 v12, -v8, v11, v10
	v_fmac_f32_e32 v11, v12, v9
	v_fma_f32 v8, -v8, v11, v10
	v_div_fmas_f32 v8, v8, v9, v11
	v_div_fixup_f32 v26, v8, v22, v18
	v_div_scale_f32 v8, s[0:1], v23, v23, v19
	v_rcp_f32_e32 v9, v8
	s_nop 0
	v_fma_f32 v10, -v8, v9, 1.0
	v_fmac_f32_e32 v9, v10, v9
	v_div_scale_f32 v10, vcc, v19, v23, v19
	v_mul_f32_e32 v11, v10, v9
	v_fma_f32 v12, -v8, v11, v10
	v_fmac_f32_e32 v11, v12, v9
	v_fma_f32 v8, -v8, v11, v10
	v_div_fmas_f32 v8, v8, v9, v11
	v_div_fixup_f32 v27, v8, v23, v19
	v_mul_f32_e32 v24, v24, v52
	v_mul_f32_e32 v25, v25, v53
	v_mul_f32_e32 v26, v26, v54
	v_mul_f32_e32 v27, v27, v55
	v_mul_f32_e32 v24, v24, v6
	v_mul_f32_e32 v25, v25, v6
	v_mul_f32_e32 v26, v26, v6
	v_mul_f32_e32 v27, v27, v6
	v_cvt_pk_bf16_f32 v30, v24, v25
	v_cvt_pk_bf16_f32 v31, v26, v27
	global_store_dwordx2 v2, v[30:31], s[88:89] offset:80
	s_waitcnt vmcnt(7)
	v_lshlrev_b32_e32 v16, 16, v76
	v_and_b32_e32 v17, 0xffff0000, v76
	v_lshlrev_b32_e32 v18, 16, v77
	v_and_b32_e32 v19, 0xffff0000, v77
	v_mul_f32_e32 v20, 0xbfb8aa3b, v16
	v_mul_f32_e32 v21, 0xbfb8aa3b, v17
	v_mul_f32_e32 v22, 0xbfb8aa3b, v18
	v_mul_f32_e32 v23, 0xbfb8aa3b, v19
	v_exp_f32_e32 v20, v20
	v_exp_f32_e32 v21, v21
	v_exp_f32_e32 v22, v22
	v_exp_f32_e32 v23, v23
	s_nop 0
	v_add_f32_e32 v20, 1.0, v20
	v_add_f32_e32 v21, 1.0, v21
	v_add_f32_e32 v22, 1.0, v22
	v_add_f32_e32 v23, 1.0, v23
	v_div_scale_f32 v8, s[0:1], v20, v20, v16
	v_rcp_f32_e32 v9, v8
	s_nop 0
	v_fma_f32 v10, -v8, v9, 1.0
	v_fmac_f32_e32 v9, v10, v9
	v_div_scale_f32 v10, vcc, v16, v20, v16
	v_mul_f32_e32 v11, v10, v9
	v_fma_f32 v12, -v8, v11, v10
	v_fmac_f32_e32 v11, v12, v9
	v_fma_f32 v8, -v8, v11, v10
	v_div_fmas_f32 v8, v8, v9, v11
	v_div_fixup_f32 v24, v8, v20, v16
	v_div_scale_f32 v8, s[0:1], v21, v21, v17
	v_rcp_f32_e32 v9, v8
	s_nop 0
	v_fma_f32 v10, -v8, v9, 1.0
	v_fmac_f32_e32 v9, v10, v9
	v_div_scale_f32 v10, vcc, v17, v21, v17
	v_mul_f32_e32 v11, v10, v9
	v_fma_f32 v12, -v8, v11, v10
	v_fmac_f32_e32 v11, v12, v9
	v_fma_f32 v8, -v8, v11, v10
	v_div_fmas_f32 v8, v8, v9, v11
	v_div_fixup_f32 v25, v8, v21, v17
	v_div_scale_f32 v8, s[0:1], v22, v22, v18
	v_rcp_f32_e32 v9, v8
	s_nop 0
	v_fma_f32 v10, -v8, v9, 1.0
	v_fmac_f32_e32 v9, v10, v9
	v_div_scale_f32 v10, vcc, v18, v22, v18
	v_mul_f32_e32 v11, v10, v9
	v_fma_f32 v12, -v8, v11, v10
	v_fmac_f32_e32 v11, v12, v9
	v_fma_f32 v8, -v8, v11, v10
	v_div_fmas_f32 v8, v8, v9, v11
	v_div_fixup_f32 v26, v8, v22, v18
	v_div_scale_f32 v8, s[0:1], v23, v23, v19
	v_rcp_f32_e32 v9, v8
	s_nop 0
	v_fma_f32 v10, -v8, v9, 1.0
	v_fmac_f32_e32 v9, v10, v9
	v_div_scale_f32 v10, vcc, v19, v23, v19
	v_mul_f32_e32 v11, v10, v9
	v_fma_f32 v12, -v8, v11, v10
	v_fmac_f32_e32 v11, v12, v9
	v_fma_f32 v8, -v8, v11, v10
	v_div_fmas_f32 v8, v8, v9, v11
	v_div_fixup_f32 v27, v8, v23, v19
	v_mul_f32_e32 v24, v24, v56
	v_mul_f32_e32 v25, v25, v57
	v_mul_f32_e32 v26, v26, v58
	v_mul_f32_e32 v27, v27, v59
	v_mul_f32_e32 v24, v24, v6
	v_mul_f32_e32 v25, v25, v6
	v_mul_f32_e32 v26, v26, v6
	v_mul_f32_e32 v27, v27, v6
	v_cvt_pk_bf16_f32 v28, v24, v25
	v_cvt_pk_bf16_f32 v29, v26, v27
	global_store_dwordx2 v2, v[28:29], s[88:89] offset:96
	s_waitcnt vmcnt(7)
	v_lshlrev_b32_e32 v16, 16, v78
	v_and_b32_e32 v17, 0xffff0000, v78
	v_lshlrev_b32_e32 v18, 16, v79
	v_and_b32_e32 v19, 0xffff0000, v79
	v_mul_f32_e32 v20, 0xbfb8aa3b, v16
	v_mul_f32_e32 v21, 0xbfb8aa3b, v17
	v_mul_f32_e32 v22, 0xbfb8aa3b, v18
	v_mul_f32_e32 v23, 0xbfb8aa3b, v19
	v_exp_f32_e32 v20, v20
	v_exp_f32_e32 v21, v21
	v_exp_f32_e32 v22, v22
	v_exp_f32_e32 v23, v23
	s_nop 0
	v_add_f32_e32 v20, 1.0, v20
	v_add_f32_e32 v21, 1.0, v21
	v_add_f32_e32 v22, 1.0, v22
	v_add_f32_e32 v23, 1.0, v23
	v_div_scale_f32 v8, s[0:1], v20, v20, v16
	v_rcp_f32_e32 v9, v8
	s_nop 0
	v_fma_f32 v10, -v8, v9, 1.0
	v_fmac_f32_e32 v9, v10, v9
	v_div_scale_f32 v10, vcc, v16, v20, v16
	v_mul_f32_e32 v11, v10, v9
	v_fma_f32 v12, -v8, v11, v10
	v_fmac_f32_e32 v11, v12, v9
	v_fma_f32 v8, -v8, v11, v10
	v_div_fmas_f32 v8, v8, v9, v11
	v_div_fixup_f32 v24, v8, v20, v16
	v_div_scale_f32 v8, s[0:1], v21, v21, v17
	v_rcp_f32_e32 v9, v8
	s_nop 0
	v_fma_f32 v10, -v8, v9, 1.0
	v_fmac_f32_e32 v9, v10, v9
	v_div_scale_f32 v10, vcc, v17, v21, v17
	v_mul_f32_e32 v11, v10, v9
	v_fma_f32 v12, -v8, v11, v10
	v_fmac_f32_e32 v11, v12, v9
	v_fma_f32 v8, -v8, v11, v10
	v_div_fmas_f32 v8, v8, v9, v11
	v_div_fixup_f32 v25, v8, v21, v17
	v_div_scale_f32 v8, s[0:1], v22, v22, v18
	v_rcp_f32_e32 v9, v8
	s_nop 0
	v_fma_f32 v10, -v8, v9, 1.0
	v_fmac_f32_e32 v9, v10, v9
	v_div_scale_f32 v10, vcc, v18, v22, v18
	v_mul_f32_e32 v11, v10, v9
	v_fma_f32 v12, -v8, v11, v10
	v_fmac_f32_e32 v11, v12, v9
	v_fma_f32 v8, -v8, v11, v10
	v_div_fmas_f32 v8, v8, v9, v11
	v_div_fixup_f32 v26, v8, v22, v18
	v_div_scale_f32 v8, s[0:1], v23, v23, v19
	v_rcp_f32_e32 v9, v8
	s_nop 0
	v_fma_f32 v10, -v8, v9, 1.0
	v_fmac_f32_e32 v9, v10, v9
	v_div_scale_f32 v10, vcc, v19, v23, v19
	v_mul_f32_e32 v11, v10, v9
	v_fma_f32 v12, -v8, v11, v10
	v_fmac_f32_e32 v11, v12, v9
	v_fma_f32 v8, -v8, v11, v10
	v_div_fmas_f32 v8, v8, v9, v11
	v_div_fixup_f32 v27, v8, v23, v19
	v_mul_f32_e32 v24, v24, v60
	v_mul_f32_e32 v25, v25, v61
	v_mul_f32_e32 v26, v26, v62
	v_mul_f32_e32 v27, v27, v63
	v_mul_f32_e32 v24, v24, v6
	v_mul_f32_e32 v25, v25, v6
	v_mul_f32_e32 v26, v26, v6
	v_mul_f32_e32 v27, v27, v6
	v_cvt_pk_bf16_f32 v30, v24, v25
	v_cvt_pk_bf16_f32 v31, v26, v27
	global_store_dwordx2 v2, v[30:31], s[88:89] offset:112
	s_add_i32 s2, s2, s71
	v_readlane_b32 s0, v206, 49
	s_nop 0
	s_cmp_ge_u32 s2, s0
	s_cbranch_scc0 .LBB0_350
	s_branch .LBB0_343
.Lat_stab_a0:
	v_sub_f32_e32 v0, v0, v129
	v_sub_f32_e32 v1, v1, v129
	v_sub_f32_e32 v2, v2, v129
	v_sub_f32_e32 v3, v3, v129
	v_sub_f32_e32 v4, v4, v129
	v_sub_f32_e32 v5, v5, v129
	v_sub_f32_e32 v6, v6, v129
	v_sub_f32_e32 v7, v7, v129
	v_sub_f32_e32 v8, v8, v129
	v_sub_f32_e32 v9, v9, v129
	v_sub_f32_e32 v10, v10, v129
	v_sub_f32_e32 v11, v11, v129
	v_sub_f32_e32 v12, v12, v129
	v_sub_f32_e32 v13, v13, v129
	v_sub_f32_e32 v14, v14, v129
	v_sub_f32_e32 v15, v15, v129
	s_branch .Lat_stab_a0_ret
.Lat_stab_b0:
	v_sub_f32_e32 v16, v16, v129
	v_sub_f32_e32 v17, v17, v129
	v_sub_f32_e32 v18, v18, v129
	v_sub_f32_e32 v19, v19, v129
	v_sub_f32_e32 v20, v20, v129
	v_sub_f32_e32 v21, v21, v129
	v_sub_f32_e32 v22, v22, v129
	v_sub_f32_e32 v23, v23, v129
	v_sub_f32_e32 v24, v24, v129
	v_sub_f32_e32 v25, v25, v129
	v_sub_f32_e32 v26, v26, v129
	v_sub_f32_e32 v27, v27, v129
	v_sub_f32_e32 v28, v28, v129
	v_sub_f32_e32 v29, v29, v129
	v_sub_f32_e32 v30, v30, v129
	v_sub_f32_e32 v31, v31, v129
	s_branch .Lat_stab_b0_ret
.Lat_rare0:
	v_max_f32_e32 v167, v0, v0
	v_max_f32_e32 v168, v16, v16
	v_max_f32_e32 v167, v167, v168
	v_max3_f32 v167, v167, v1, v17
	v_max3_f32 v167, v167, v2, v18
	v_max3_f32 v167, v167, v3, v19
	v_max3_f32 v167, v167, v4, v20
	v_max3_f32 v167, v167, v5, v21
	v_max3_f32 v167, v167, v6, v22
	v_max3_f32 v167, v167, v7, v23
	v_max3_f32 v167, v167, v8, v24
	v_max3_f32 v167, v167, v9, v25
	v_max3_f32 v167, v167, v10, v26
	v_max3_f32 v167, v167, v11, v27
	v_max3_f32 v167, v167, v12, v28
	v_max3_f32 v167, v167, v13, v29
	v_max3_f32 v167, v167, v14, v30
	v_max3_f32 v167, v167, v15, v31
	v_mbcnt_lo_u32_b32 v168, -1, 0
	v_mbcnt_hi_u32_b32 v168, -1, v168
	v_xor_b32_e32 v168, 32, v168
	v_lshlrev_b32_e32 v168, 2, v168
	ds_bpermute_b32 v169, v168, v167
	ds_bpermute_b32 v170, v168, v128
	s_mov_b32 s84, 1
	s_waitcnt lgkmcnt(1)
	v_max_f32_e32 v169, v169, v169
	v_max_f32_e32 v167, v167, v169
	s_waitcnt lgkmcnt(0)
	v_add_f32_e32 v170, v128, v170
	v_max_f32_e32 v169, 0, v167
	v_cmp_nle_f32_e32 vcc, s73, v170
	s_nop 1
	v_cndmask_b32_e32 v171, v169, v167, vcc
	v_exp_f32_e64 v172, -v171
	s_nop 0
	v_cndmask_b32_e64 v172, v172, 0, vcc
	v_add_f32_e32 v129, v129, v171
	v_mul_f32_e32 v128, v128, v172
	v_mul_f32_e32 v32, v32, v172
	v_mul_f32_e32 v33, v33, v172
	v_mul_f32_e32 v34, v34, v172
	v_mul_f32_e32 v35, v35, v172
	v_mul_f32_e32 v36, v36, v172
	v_mul_f32_e32 v37, v37, v172
	v_mul_f32_e32 v38, v38, v172
	v_mul_f32_e32 v39, v39, v172
	v_mul_f32_e32 v40, v40, v172
	v_mul_f32_e32 v41, v41, v172
	v_mul_f32_e32 v42, v42, v172
	v_mul_f32_e32 v43, v43, v172
	v_mul_f32_e32 v44, v44, v172
	v_mul_f32_e32 v45, v45, v172
	v_mul_f32_e32 v46, v46, v172
	v_mul_f32_e32 v47, v47, v172
	v_mul_f32_e32 v48, v48, v172
	v_mul_f32_e32 v49, v49, v172
	v_mul_f32_e32 v50, v50, v172
	v_mul_f32_e32 v51, v51, v172
	v_mul_f32_e32 v52, v52, v172
	v_mul_f32_e32 v53, v53, v172
	v_mul_f32_e32 v54, v54, v172
	v_mul_f32_e32 v55, v55, v172
	v_mul_f32_e32 v56, v56, v172
	v_mul_f32_e32 v57, v57, v172
	v_mul_f32_e32 v58, v58, v172
	v_mul_f32_e32 v59, v59, v172
	v_mul_f32_e32 v60, v60, v172
	v_mul_f32_e32 v61, v61, v172
	v_mul_f32_e32 v62, v62, v172
	v_mul_f32_e32 v63, v63, v172
	v_sub_f32_e32 v174, v0, v171
	v_exp_f32_e32 v64, v174
	v_sub_f32_e32 v174, v1, v171
	v_exp_f32_e32 v65, v174
	v_add_f32_e32 v136, 0, v64
	v_sub_f32_e32 v174, v2, v171
	v_exp_f32_e32 v66, v174
	v_add_f32_e32 v136, v65, v136
	v_sub_f32_e32 v174, v3, v171
	v_exp_f32_e32 v67, v174
	v_add_f32_e32 v136, v66, v136
	v_sub_f32_e32 v174, v4, v171
	v_exp_f32_e32 v68, v174
	v_add_f32_e32 v136, v67, v136
	v_sub_f32_e32 v174, v5, v171
	v_exp_f32_e32 v69, v174
	v_add_f32_e32 v136, v68, v136
	v_sub_f32_e32 v174, v6, v171
	v_exp_f32_e32 v70, v174
	v_add_f32_e32 v136, v69, v136
	v_sub_f32_e32 v174, v7, v171
	v_exp_f32_e32 v71, v174
	v_add_f32_e32 v136, v70, v136
	v_sub_f32_e32 v174, v8, v171
	v_exp_f32_e32 v72, v174
	v_add_f32_e32 v136, v71, v136
	v_sub_f32_e32 v174, v9, v171
	v_exp_f32_e32 v73, v174
	v_add_f32_e32 v136, v72, v136
	v_sub_f32_e32 v174, v10, v171
	v_exp_f32_e32 v74, v174
	v_add_f32_e32 v136, v73, v136
	v_sub_f32_e32 v174, v11, v171
	v_exp_f32_e32 v75, v174
	v_add_f32_e32 v136, v74, v136
	v_sub_f32_e32 v174, v12, v171
	v_exp_f32_e32 v76, v174
	v_add_f32_e32 v136, v75, v136
	v_sub_f32_e32 v174, v13, v171
	v_exp_f32_e32 v77, v174
	v_add_f32_e32 v136, v76, v136
	v_sub_f32_e32 v174, v14, v171
	v_exp_f32_e32 v78, v174
	v_add_f32_e32 v136, v77, v136
	v_sub_f32_e32 v174, v15, v171
	v_exp_f32_e32 v79, v174
	v_add_f32_e32 v136, v78, v136
	s_nop 0
	v_add_f32_e32 v136, v79, v136
	v_sub_f32_e32 v174, v16, v171
	v_exp_f32_e32 v80, v174
	v_sub_f32_e32 v174, v17, v171
	v_exp_f32_e32 v81, v174
	v_add_f32_e32 v137, 0, v80
	v_sub_f32_e32 v174, v18, v171
	v_exp_f32_e32 v82, v174
	v_add_f32_e32 v137, v81, v137
	v_sub_f32_e32 v174, v19, v171
	v_exp_f32_e32 v83, v174
	v_add_f32_e32 v137, v82, v137
	v_sub_f32_e32 v174, v20, v171
	v_exp_f32_e32 v84, v174
	v_add_f32_e32 v137, v83, v137
	v_sub_f32_e32 v174, v21, v171
	v_exp_f32_e32 v85, v174
	v_add_f32_e32 v137, v84, v137
	v_sub_f32_e32 v174, v22, v171
	v_exp_f32_e32 v86, v174
	v_add_f32_e32 v137, v85, v137
	v_sub_f32_e32 v174, v23, v171
	v_exp_f32_e32 v87, v174
	v_add_f32_e32 v137, v86, v137
	v_sub_f32_e32 v174, v24, v171
	v_exp_f32_e32 v88, v174
	v_add_f32_e32 v137, v87, v137
	v_sub_f32_e32 v174, v25, v171
	v_exp_f32_e32 v89, v174
	v_add_f32_e32 v137, v88, v137
	v_sub_f32_e32 v174, v26, v171
	v_exp_f32_e32 v90, v174
	v_add_f32_e32 v137, v89, v137
	v_sub_f32_e32 v174, v27, v171
	v_exp_f32_e32 v91, v174
	v_add_f32_e32 v137, v90, v137
	v_sub_f32_e32 v174, v28, v171
	v_exp_f32_e32 v92, v174
	v_add_f32_e32 v137, v91, v137
	v_sub_f32_e32 v174, v29, v171
	v_exp_f32_e32 v93, v174
	v_add_f32_e32 v137, v92, v137
	v_sub_f32_e32 v174, v30, v171
	v_exp_f32_e32 v94, v174
	v_add_f32_e32 v137, v93, v137
	v_sub_f32_e32 v174, v31, v171
	v_exp_f32_e32 v95, v174
	v_add_f32_e32 v137, v94, v137
	s_nop 0
	v_add_f32_e32 v137, v95, v137
	v_add_f32_e32 v134, v136, v137
	s_branch .Lat_rare0_ret

	.amdhsa_kernel _Z14fwd_megakernel6Params
		.amdhsa_group_segment_fixed_size 73744
		.amdhsa_private_segment_fixed_size 0
		.amdhsa_kernarg_size 408
		.amdhsa_user_sgpr_count 2
		.amdhsa_user_sgpr_dispatch_ptr 0
		.amdhsa_user_sgpr_queue_ptr 0
		.amdhsa_user_sgpr_kernarg_segment_ptr 1
		.amdhsa_user_sgpr_dispatch_id 0
		.amdhsa_user_sgpr_kernarg_preload_length 0
		.amdhsa_user_sgpr_kernarg_preload_offset 0
		.amdhsa_user_sgpr_private_segment_size 0
		.amdhsa_uses_dynamic_stack 0
		.amdhsa_enable_private_segment 0
		.amdhsa_system_sgpr_workgroup_id_x 1
		.amdhsa_system_sgpr_workgroup_id_y 0
		.amdhsa_system_sgpr_workgroup_id_z 0
		.amdhsa_system_sgpr_workgroup_info 0
		.amdhsa_system_vgpr_workitem_id 2
		.amdhsa_next_free_vgpr 256
		.amdhsa_next_free_sgpr 98
		.amdhsa_accum_offset 256
		.amdhsa_reserve_vcc 1
		.amdhsa_float_round_mode_32 0
		.amdhsa_float_round_mode_16_64 0
		.amdhsa_float_denorm_mode_32 3
		.amdhsa_float_denorm_mode_16_64 3
		.amdhsa_dx10_clamp 1
		.amdhsa_ieee_mode 1
		.amdhsa_fp16_overflow 0
		.amdhsa_tg_split 0
		.amdhsa_exception_fp_ieee_invalid_op 0
		.amdhsa_exception_fp_denorm_src 0
		.amdhsa_exception_fp_ieee_div_zero 0
		.amdhsa_exception_fp_ieee_overflow 0
		.amdhsa_exception_fp_ieee_underflow 0
		.amdhsa_exception_fp_ieee_inexact 0
		.amdhsa_exception_int_div_zero 0
	.end_amdhsa_kernel

.Lfunc_end0:
	.size	_Z14fwd_megakernel6Params, .Lfunc_end0-_Z14fwd_megakernel6Params
	.set _Z14fwd_megakernel6Params.num_vgpr, 256
	.set _Z14fwd_megakernel6Params.num_agpr, 0
	.set _Z14fwd_megakernel6Params.numbered_sgpr, 98
	.set _Z14fwd_megakernel6Params.num_named_barrier, 0
	.set _Z14fwd_megakernel6Params.private_seg_size, 0
	.set _Z14fwd_megakernel6Params.uses_vcc, 1
	.set _Z14fwd_megakernel6Params.uses_flat_scratch, 0
	.set _Z14fwd_megakernel6Params.has_dyn_sized_stack, 0
	.set _Z14fwd_megakernel6Params.has_recursion, 0
	.set _Z14fwd_megakernel6Params.has_indirect_call, 0

amdhsa.kernels:
  - .agpr_count:     0
    .args:
      - .offset:         0
        .size:           152
        .value_kind:     by_value
      - .offset:         152
        .size:           4
        .value_kind:     hidden_block_count_x
      - .offset:         156
        .size:           4
        .value_kind:     hidden_block_count_y
      - .offset:         160
        .size:           4
        .value_kind:     hidden_block_count_z
      - .offset:         164
        .size:           2
        .value_kind:     hidden_group_size_x
      - .offset:         166
        .size:           2
        .value_kind:     hidden_group_size_y
      - .offset:         168
        .size:           2
        .value_kind:     hidden_group_size_z
      - .offset:         170
        .size:           2
        .value_kind:     hidden_remainder_x
      - .offset:         172
        .size:           2
        .value_kind:     hidden_remainder_y
      - .offset:         174
        .size:           2
        .value_kind:     hidden_remainder_z
      - .offset:         192
        .size:           8
        .value_kind:     hidden_global_offset_x
      - .offset:         200
        .size:           8
        .value_kind:     hidden_global_offset_y
      - .offset:         208
        .size:           8
        .value_kind:     hidden_global_offset_z
      - .offset:         216
        .size:           2
        .value_kind:     hidden_grid_dims
      - .offset:         240
        .size:           8
        .value_kind:     hidden_multigrid_sync_arg
    .group_segment_fixed_size: 73744
    .kernarg_segment_align: 8
    .kernarg_segment_size: 408
    .language:       OpenCL C
    .language_version:
      - 2
      - 0
    .max_flat_workgroup_size: 256
    .name:           _Z14fwd_megakernel6Params
    .private_segment_fixed_size: 0
    .sgpr_count:     104
    .sgpr_spill_count: 151
    .symbol:         _Z14fwd_megakernel6Params.kd
    .uniform_work_group_size: 1
    .uses_dynamic_stack: false
    .vgpr_count:     256
    .vgpr_spill_count: 0
    .wavefront_size: 64
